# plus transposes on idle P1-tail WGs 73-179 and layer-2 prefetch
# baseline (speedup 1.0000x reference)
.LBB0_325:
	s_cmp_lt_u32 s2, 73
	s_cbranch_scc1 .Lrc_p1skip
	s_cmp_ge_u32 s2, 180
	s_cbranch_scc1 .Lrc_p1pg
	s_mov_b64 exec, -1
	v_readlane_b32 s0, v254, 0
	v_readlane_b32 s1, v254, 1
	s_nop 4
	s_load_dwordx2 s[56:57], s[0:1], 0xa8
	s_load_dwordx2 s[58:59], s[0:1], 0xc0
	s_load_dwordx2 s[60:61], s[0:1], 0x88
	s_load_dwordx2 s[62:63], s[0:1], 0x78
	s_load_dwordx2 s[64:65], s[0:1], 0x80
	s_load_dwordx2 s[66:67], s[0:1], 0x90
	s_load_dwordx2 s[68:69], s[0:1], 0xa0
	s_load_dwordx2 s[70:71], s[0:1], 0x48
	s_load_dwordx2 s[72:73], s[0:1], 0xd8
	s_load_dword s3, s[0:1], 0xe8
	v_readfirstlane_b32 s4, v0
	v_and_b32_e32 v7, 63, v0
	s_lshr_b32 s4, s4, 6
	v_lshrrev_b32_e32 v1, 3, v7
	v_and_b32_e32 v2, 7, v7
	s_lshl_b32 s5, s4, 14
	v_lshlrev_b32_e32 v5, 5, v2
	s_movk_i32 s14, 0x420
	v_mul_u32_u24_e32 v4, s14, v2
	v_lshlrev_b32_e32 v2, 4, v2
	s_movk_i32 s14, 0x84
	v_mad_u32_u24 v3, v1, s14, v2
	v_lshl_add_u32 v4, v1, 2, v4
	v_add_u32_e32 v3, s5, v3
	v_add_u32_e32 v4, s5, v4
	v_mov_b32_e32 v207, v3
	v_add_u32_e32 v208, 1056, v3
	v_add_u32_e32 v209, 2112, v3
	v_add_u32_e32 v210, 3168, v3
	v_add_u32_e32 v211, 4224, v3
	v_add_u32_e32 v212, 5280, v3
	v_add_u32_e32 v213, 6336, v3
	v_add_u32_e32 v214, 7392, v3
	s_waitcnt lgkmcnt(0)
	s_sub_u32 s5, s2, 73
	s_lshl_b32 s5, s5, 3
	s_add_u32 s20, s5, s4
	s_movk_i32 s21, 856
	s_cmp_ge_u32 s20, 0x10b8
	s_cbranch_scc1 .Lrc_p1skip
	s_mov_b32 s42, 0
	s_mov_b32 s43, 0
	s_mov_b32 s26, s20
	s_cmp_lt_u32 s26, 0x2c00
	s_cbranch_scc1 .Ltrp1_i1_s0
	s_sub_u32 s26, s26, 0x2c00
	s_cmp_lt_u32 s26, 0x1600
	s_cbranch_scc1 .Ltrp1_i1_s1
	s_sub_u32 s26, s26, 0x1600
	s_cmp_lt_u32 s26, 0x800
	s_cbranch_scc1 .Ltrp1_i1_s2
	s_sub_u32 s26, s26, 0x800
	s_cmp_lt_u32 s26, 0x400
	s_cbranch_scc1 .Ltrp1_i1_s3
	s_sub_u32 s26, s26, 0x400
	s_cmp_lt_u32 s26, 0x400
	s_cbranch_scc1 .Ltrp1_i1_s4
	s_sub_u32 s26, s26, 0x400
	s_cmp_lt_u32 s26, 0x200
	s_cbranch_scc1 .Ltrp1_i1_s5
	s_sub_u32 s26, s26, 0x200
	s_branch .Ltrp1_i1_s6

.Ltrp1_i1_c:
	s_lshl_b32 s4, s24, 6
	s_mul_i32 s4, s25, s4
	s_lshl_b32 s5, s27, 7
	s_add_u32 s4, s4, s5
	s_add_u32 s10, s22, s4
	s_addc_u32 s11, s23, 0
	v_mad_u32_u24 v6, v1, s24, v2
	s_lshl_b32 s4, s29, 5
	s_mul_i32 s4, s27, s4
	s_lshl_b32 s5, s25, 7
	s_add_u32 s4, s4, s5
	s_add_u32 s4, s4, s28
	s_add_u32 s74, s72, s4
	s_addc_u32 s75, s73, 0
	s_mov_b32 s76, s29
	s_mov_b32 s77, s31
	s_lshl_b32 s4, s25, 8
	s_add_u32 s4, s4, s30
	s_add_u32 s12, s70, s4
	s_addc_u32 s13, s71, 0
	s_lshl_b32 s14, s24, 3
	global_load_dwordx4 v[44:47], v6, s[10:11]
	s_add_u32 s10, s10, s14
	s_addc_u32 s11, s11, 0
	global_load_dwordx4 v[48:51], v6, s[10:11]
	s_add_u32 s10, s10, s14
	s_addc_u32 s11, s11, 0
	global_load_dwordx4 v[52:55], v6, s[10:11]
	s_add_u32 s10, s10, s14
	s_addc_u32 s11, s11, 0
	global_load_dwordx4 v[56:59], v6, s[10:11]
	s_add_u32 s10, s10, s14
	s_addc_u32 s11, s11, 0
	global_load_dwordx4 v[60:63], v6, s[10:11]
	s_add_u32 s10, s10, s14
	s_addc_u32 s11, s11, 0
	global_load_dwordx4 v[64:67], v6, s[10:11]
	s_add_u32 s10, s10, s14
	s_addc_u32 s11, s11, 0
	global_load_dwordx4 v[68:71], v6, s[10:11]
	s_add_u32 s10, s10, s14
	s_addc_u32 s11, s11, 0
	global_load_dwordx4 v[72:75], v6, s[10:11]
	global_load_dwordx4 v[76:79], v5, s[12:13]
	global_load_dwordx4 v[80:83], v5, s[12:13] offset:16
	s_add_u32 s20, s20, s21
	s_add_u32 s42, s42, 1
	s_cmp_ge_u32 s20, 0x10b8
	s_cbranch_scc1 .Ltrp1_st0
	s_mov_b32 s26, s20
	s_cmp_lt_u32 s26, 0x2c00
	s_cbranch_scc1 .Ltrp1_i2_s0
	s_sub_u32 s26, s26, 0x2c00
	s_cmp_lt_u32 s26, 0x1600
	s_cbranch_scc1 .Ltrp1_i2_s1
	s_sub_u32 s26, s26, 0x1600
	s_cmp_lt_u32 s26, 0x800
	s_cbranch_scc1 .Ltrp1_i2_s2
	s_sub_u32 s26, s26, 0x800
	s_cmp_lt_u32 s26, 0x400
	s_cbranch_scc1 .Ltrp1_i2_s3
	s_sub_u32 s26, s26, 0x400
	s_cmp_lt_u32 s26, 0x400
	s_cbranch_scc1 .Ltrp1_i2_s4
	s_sub_u32 s26, s26, 0x400
	s_cmp_lt_u32 s26, 0x200
	s_cbranch_scc1 .Ltrp1_i2_s5
	s_sub_u32 s26, s26, 0x200
	s_branch .Ltrp1_i2_s6

.Ltrp1_i2_c:
	s_lshl_b32 s4, s24, 6
	s_mul_i32 s4, s25, s4
	s_lshl_b32 s5, s27, 7
	s_add_u32 s4, s4, s5
	s_add_u32 s10, s22, s4
	s_addc_u32 s11, s23, 0
	v_mad_u32_u24 v6, v1, s24, v2
	s_lshl_b32 s4, s29, 5
	s_mul_i32 s4, s27, s4
	s_lshl_b32 s5, s25, 7
	s_add_u32 s4, s4, s5
	s_add_u32 s4, s4, s28
	s_add_u32 s78, s72, s4
	s_addc_u32 s79, s73, 0
	s_mov_b32 s80, s29
	s_mov_b32 s81, s31
	s_lshl_b32 s4, s25, 8
	s_add_u32 s4, s4, s30
	s_add_u32 s12, s70, s4
	s_addc_u32 s13, s71, 0
	s_lshl_b32 s14, s24, 3
	global_load_dwordx4 v[84:87], v6, s[10:11]
	s_add_u32 s10, s10, s14
	s_addc_u32 s11, s11, 0
	global_load_dwordx4 v[88:91], v6, s[10:11]
	s_add_u32 s10, s10, s14
	s_addc_u32 s11, s11, 0
	global_load_dwordx4 v[92:95], v6, s[10:11]
	s_add_u32 s10, s10, s14
	s_addc_u32 s11, s11, 0
	global_load_dwordx4 v[96:99], v6, s[10:11]
	s_add_u32 s10, s10, s14
	s_addc_u32 s11, s11, 0
	global_load_dwordx4 v[100:103], v6, s[10:11]
	s_add_u32 s10, s10, s14
	s_addc_u32 s11, s11, 0
	global_load_dwordx4 v[104:107], v6, s[10:11]
	s_add_u32 s10, s10, s14
	s_addc_u32 s11, s11, 0
	global_load_dwordx4 v[108:111], v6, s[10:11]
	s_add_u32 s10, s10, s14
	s_addc_u32 s11, s11, 0
	global_load_dwordx4 v[112:115], v6, s[10:11]
	global_load_dwordx4 v[116:119], v5, s[12:13]
	global_load_dwordx4 v[120:123], v5, s[12:13] offset:16
	s_add_u32 s20, s20, s21
	s_add_u32 s42, s42, 1
	s_cmp_ge_u32 s20, 0x10b8
	s_cbranch_scc1 .Ltrp1_st0
	s_mov_b32 s26, s20
	s_cmp_lt_u32 s26, 0x2c00
	s_cbranch_scc1 .Ltrp1_i3_s0
	s_sub_u32 s26, s26, 0x2c00
	s_cmp_lt_u32 s26, 0x1600
	s_cbranch_scc1 .Ltrp1_i3_s1
	s_sub_u32 s26, s26, 0x1600
	s_cmp_lt_u32 s26, 0x800
	s_cbranch_scc1 .Ltrp1_i3_s2
	s_sub_u32 s26, s26, 0x800
	s_cmp_lt_u32 s26, 0x400
	s_cbranch_scc1 .Ltrp1_i3_s3
	s_sub_u32 s26, s26, 0x400
	s_cmp_lt_u32 s26, 0x400
	s_cbranch_scc1 .Ltrp1_i3_s4
	s_sub_u32 s26, s26, 0x400
	s_cmp_lt_u32 s26, 0x200
	s_cbranch_scc1 .Ltrp1_i3_s5
	s_sub_u32 s26, s26, 0x200
	s_branch .Ltrp1_i3_s6

.Ltrp1_i3_c:
	s_lshl_b32 s4, s24, 6
	s_mul_i32 s4, s25, s4
	s_lshl_b32 s5, s27, 7
	s_add_u32 s4, s4, s5
	s_add_u32 s10, s22, s4
	s_addc_u32 s11, s23, 0
	v_mad_u32_u24 v6, v1, s24, v2
	s_lshl_b32 s4, s29, 5
	s_mul_i32 s4, s27, s4
	s_lshl_b32 s5, s25, 7
	s_add_u32 s4, s4, s5
	s_add_u32 s4, s4, s28
	s_add_u32 s82, s72, s4
	s_addc_u32 s83, s73, 0
	s_mov_b32 s84, s29
	s_mov_b32 s85, s31
	s_lshl_b32 s4, s25, 8
	s_add_u32 s4, s4, s30
	s_add_u32 s12, s70, s4
	s_addc_u32 s13, s71, 0
	s_lshl_b32 s14, s24, 3
	global_load_dwordx4 v[124:127], v6, s[10:11]
	s_add_u32 s10, s10, s14
	s_addc_u32 s11, s11, 0
	global_load_dwordx4 v[128:131], v6, s[10:11]
	s_add_u32 s10, s10, s14
	s_addc_u32 s11, s11, 0
	global_load_dwordx4 v[132:135], v6, s[10:11]
	s_add_u32 s10, s10, s14
	s_addc_u32 s11, s11, 0
	global_load_dwordx4 v[136:139], v6, s[10:11]
	s_add_u32 s10, s10, s14
	s_addc_u32 s11, s11, 0
	global_load_dwordx4 v[140:143], v6, s[10:11]
	s_add_u32 s10, s10, s14
	s_addc_u32 s11, s11, 0
	global_load_dwordx4 v[144:147], v6, s[10:11]
	s_add_u32 s10, s10, s14
	s_addc_u32 s11, s11, 0
	global_load_dwordx4 v[148:151], v6, s[10:11]
	s_add_u32 s10, s10, s14
	s_addc_u32 s11, s11, 0
	global_load_dwordx4 v[152:155], v6, s[10:11]
	global_load_dwordx4 v[156:159], v5, s[12:13]
	global_load_dwordx4 v[160:163], v5, s[12:13] offset:16
	s_add_u32 s20, s20, s21
	s_add_u32 s42, s42, 1
	s_cmp_ge_u32 s20, 0x10b8
	s_cbranch_scc1 .Ltrp1_st0
	s_mov_b32 s26, s20
	s_cmp_lt_u32 s26, 0x2c00
	s_cbranch_scc1 .Ltrp1_i4_s0
	s_sub_u32 s26, s26, 0x2c00
	s_cmp_lt_u32 s26, 0x1600
	s_cbranch_scc1 .Ltrp1_i4_s1
	s_sub_u32 s26, s26, 0x1600
	s_cmp_lt_u32 s26, 0x800
	s_cbranch_scc1 .Ltrp1_i4_s2
	s_sub_u32 s26, s26, 0x800
	s_cmp_lt_u32 s26, 0x400
	s_cbranch_scc1 .Ltrp1_i4_s3
	s_sub_u32 s26, s26, 0x400
	s_cmp_lt_u32 s26, 0x400
	s_cbranch_scc1 .Ltrp1_i4_s4
	s_sub_u32 s26, s26, 0x400
	s_cmp_lt_u32 s26, 0x200
	s_cbranch_scc1 .Ltrp1_i4_s5
	s_sub_u32 s26, s26, 0x200
	s_branch .Ltrp1_i4_s6

.Ltrp1_p5_ng:
	v_cvt_pk_bf16_f32 v12, v12, v13
	v_cvt_pk_bf16_f32 v13, v14, v15
	v_cvt_pk_bf16_f32 v14, v16, v17
	v_cvt_pk_bf16_f32 v15, v18, v19
	v_cvt_pk_bf16_f32 v20, v20, v21
	v_cvt_pk_bf16_f32 v21, v22, v23
	v_cvt_pk_bf16_f32 v22, v24, v25
	v_cvt_pk_bf16_f32 v23, v26, v27
	v_cvt_pk_bf16_f32 v28, v28, v29
	v_cvt_pk_bf16_f32 v29, v30, v31
	v_cvt_pk_bf16_f32 v30, v32, v33
	v_cvt_pk_bf16_f32 v31, v34, v35
	v_cvt_pk_bf16_f32 v36, v36, v37
	v_cvt_pk_bf16_f32 v37, v38, v39
	v_cvt_pk_bf16_f32 v38, v40, v41
	v_cvt_pk_bf16_f32 v39, v42, v43
	global_store_dwordx4 v8, v[12:15], s[74:75]
	global_store_dwordx4 v9, v[20:23], s[74:75]
	global_store_dwordx4 v10, v[28:31], s[74:75]
	global_store_dwordx4 v11, v[36:39], s[74:75]
	s_sub_u32 s42, s42, 1
	s_add_u32 s43, s43, 1
	s_cmp_ge_u32 s20, 0x10b8
	s_cbranch_scc1 .Ltrp1_ni_0
	s_mov_b32 s26, s20
	s_cmp_lt_u32 s26, 0x2c00
	s_cbranch_scc1 .Ltrp1_i6_s0
	s_sub_u32 s26, s26, 0x2c00
	s_cmp_lt_u32 s26, 0x1600
	s_cbranch_scc1 .Ltrp1_i6_s1
	s_sub_u32 s26, s26, 0x1600
	s_cmp_lt_u32 s26, 0x800
	s_cbranch_scc1 .Ltrp1_i6_s2
	s_sub_u32 s26, s26, 0x800
	s_cmp_lt_u32 s26, 0x400
	s_cbranch_scc1 .Ltrp1_i6_s3
	s_sub_u32 s26, s26, 0x400
	s_cmp_lt_u32 s26, 0x400
	s_cbranch_scc1 .Ltrp1_i6_s4
	s_sub_u32 s26, s26, 0x400
	s_cmp_lt_u32 s26, 0x200
	s_cbranch_scc1 .Ltrp1_i6_s5
	s_sub_u32 s26, s26, 0x200
	s_branch .Ltrp1_i6_s6

.Ltrp1_p7_ng:
	v_cvt_pk_bf16_f32 v12, v12, v13
	v_cvt_pk_bf16_f32 v13, v14, v15
	v_cvt_pk_bf16_f32 v14, v16, v17
	v_cvt_pk_bf16_f32 v15, v18, v19
	v_cvt_pk_bf16_f32 v20, v20, v21
	v_cvt_pk_bf16_f32 v21, v22, v23
	v_cvt_pk_bf16_f32 v22, v24, v25
	v_cvt_pk_bf16_f32 v23, v26, v27
	v_cvt_pk_bf16_f32 v28, v28, v29
	v_cvt_pk_bf16_f32 v29, v30, v31
	v_cvt_pk_bf16_f32 v30, v32, v33
	v_cvt_pk_bf16_f32 v31, v34, v35
	v_cvt_pk_bf16_f32 v36, v36, v37
	v_cvt_pk_bf16_f32 v37, v38, v39
	v_cvt_pk_bf16_f32 v38, v40, v41
	v_cvt_pk_bf16_f32 v39, v42, v43
	global_store_dwordx4 v8, v[12:15], s[78:79]
	global_store_dwordx4 v9, v[20:23], s[78:79]
	global_store_dwordx4 v10, v[28:31], s[78:79]
	global_store_dwordx4 v11, v[36:39], s[78:79]
	s_sub_u32 s42, s42, 1
	s_add_u32 s43, s43, 1
	s_cmp_ge_u32 s20, 0x10b8
	s_cbranch_scc1 .Ltrp1_ni_1
	s_mov_b32 s26, s20
	s_cmp_lt_u32 s26, 0x2c00
	s_cbranch_scc1 .Ltrp1_i8_s0
	s_sub_u32 s26, s26, 0x2c00
	s_cmp_lt_u32 s26, 0x1600
	s_cbranch_scc1 .Ltrp1_i8_s1
	s_sub_u32 s26, s26, 0x1600
	s_cmp_lt_u32 s26, 0x800
	s_cbranch_scc1 .Ltrp1_i8_s2
	s_sub_u32 s26, s26, 0x800
	s_cmp_lt_u32 s26, 0x400
	s_cbranch_scc1 .Ltrp1_i8_s3
	s_sub_u32 s26, s26, 0x400
	s_cmp_lt_u32 s26, 0x400
	s_cbranch_scc1 .Ltrp1_i8_s4
	s_sub_u32 s26, s26, 0x400
	s_cmp_lt_u32 s26, 0x200
	s_cbranch_scc1 .Ltrp1_i8_s5
	s_sub_u32 s26, s26, 0x200
	s_branch .Ltrp1_i8_s6

.Ltrp1_p9_ng:
	v_cvt_pk_bf16_f32 v12, v12, v13
	v_cvt_pk_bf16_f32 v13, v14, v15
	v_cvt_pk_bf16_f32 v14, v16, v17
	v_cvt_pk_bf16_f32 v15, v18, v19
	v_cvt_pk_bf16_f32 v20, v20, v21
	v_cvt_pk_bf16_f32 v21, v22, v23
	v_cvt_pk_bf16_f32 v22, v24, v25
	v_cvt_pk_bf16_f32 v23, v26, v27
	v_cvt_pk_bf16_f32 v28, v28, v29
	v_cvt_pk_bf16_f32 v29, v30, v31
	v_cvt_pk_bf16_f32 v30, v32, v33
	v_cvt_pk_bf16_f32 v31, v34, v35
	v_cvt_pk_bf16_f32 v36, v36, v37
	v_cvt_pk_bf16_f32 v37, v38, v39
	v_cvt_pk_bf16_f32 v38, v40, v41
	v_cvt_pk_bf16_f32 v39, v42, v43
	global_store_dwordx4 v8, v[12:15], s[82:83]
	global_store_dwordx4 v9, v[20:23], s[82:83]
	global_store_dwordx4 v10, v[28:31], s[82:83]
	global_store_dwordx4 v11, v[36:39], s[82:83]
	s_sub_u32 s42, s42, 1
	s_add_u32 s43, s43, 1
	s_cmp_ge_u32 s20, 0x10b8
	s_cbranch_scc1 .Ltrp1_ni_2
	s_mov_b32 s26, s20
	s_cmp_lt_u32 s26, 0x2c00
	s_cbranch_scc1 .Ltrp1_i10_s0
	s_sub_u32 s26, s26, 0x2c00
	s_cmp_lt_u32 s26, 0x1600
	s_cbranch_scc1 .Ltrp1_i10_s1
	s_sub_u32 s26, s26, 0x1600
	s_cmp_lt_u32 s26, 0x800
	s_cbranch_scc1 .Ltrp1_i10_s2
	s_sub_u32 s26, s26, 0x800
	s_cmp_lt_u32 s26, 0x400
	s_cbranch_scc1 .Ltrp1_i10_s3
	s_sub_u32 s26, s26, 0x400
	s_cmp_lt_u32 s26, 0x400
	s_cbranch_scc1 .Ltrp1_i10_s4
	s_sub_u32 s26, s26, 0x400
	s_cmp_lt_u32 s26, 0x200
	s_cbranch_scc1 .Ltrp1_i10_s5
	s_sub_u32 s26, s26, 0x200
	s_branch .Ltrp1_i10_s6

.Ltrp1_p11_ng:
	v_cvt_pk_bf16_f32 v12, v12, v13
	v_cvt_pk_bf16_f32 v13, v14, v15
	v_cvt_pk_bf16_f32 v14, v16, v17
	v_cvt_pk_bf16_f32 v15, v18, v19
	v_cvt_pk_bf16_f32 v20, v20, v21
	v_cvt_pk_bf16_f32 v21, v22, v23
	v_cvt_pk_bf16_f32 v22, v24, v25
	v_cvt_pk_bf16_f32 v23, v26, v27
	v_cvt_pk_bf16_f32 v28, v28, v29
	v_cvt_pk_bf16_f32 v29, v30, v31
	v_cvt_pk_bf16_f32 v30, v32, v33
	v_cvt_pk_bf16_f32 v31, v34, v35
	v_cvt_pk_bf16_f32 v36, v36, v37
	v_cvt_pk_bf16_f32 v37, v38, v39
	v_cvt_pk_bf16_f32 v38, v40, v41
	v_cvt_pk_bf16_f32 v39, v42, v43
	global_store_dwordx4 v8, v[12:15], s[86:87]
	global_store_dwordx4 v9, v[20:23], s[86:87]
	global_store_dwordx4 v10, v[28:31], s[86:87]
	global_store_dwordx4 v11, v[36:39], s[86:87]
	s_sub_u32 s42, s42, 1
	s_add_u32 s43, s43, 1
	s_cmp_ge_u32 s20, 0x10b8
	s_cbranch_scc1 .Ltrp1_ni_3
	s_mov_b32 s26, s20
	s_cmp_lt_u32 s26, 0x2c00
	s_cbranch_scc1 .Ltrp1_i12_s0
	s_sub_u32 s26, s26, 0x2c00
	s_cmp_lt_u32 s26, 0x1600
	s_cbranch_scc1 .Ltrp1_i12_s1
	s_sub_u32 s26, s26, 0x1600
	s_cmp_lt_u32 s26, 0x800
	s_cbranch_scc1 .Ltrp1_i12_s2
	s_sub_u32 s26, s26, 0x800
	s_cmp_lt_u32 s26, 0x400
	s_cbranch_scc1 .Ltrp1_i12_s3
	s_sub_u32 s26, s26, 0x400
	s_cmp_lt_u32 s26, 0x400
	s_cbranch_scc1 .Ltrp1_i12_s4
	s_sub_u32 s26, s26, 0x400
	s_cmp_lt_u32 s26, 0x200
	s_cbranch_scc1 .Ltrp1_i12_s5
	s_sub_u32 s26, s26, 0x200
	s_branch .Ltrp1_i12_s6

.LBB0_693:
	s_cmp_lt_u32 s2, 8
	s_barrier
	s_cbranch_scc1 .LBB0_950
	s_mov_b64 exec, -1
	v_readlane_b32 s0, v254, 0
	v_readlane_b32 s1, v254, 1
	s_nop 4
	s_load_dwordx2 s[56:57], s[0:1], 0xa8
	s_load_dwordx2 s[58:59], s[0:1], 0xc0
	s_load_dwordx2 s[60:61], s[0:1], 0x88
	s_load_dwordx2 s[62:63], s[0:1], 0x78
	s_load_dwordx2 s[64:65], s[0:1], 0x80
	s_load_dwordx2 s[66:67], s[0:1], 0x90
	s_load_dwordx2 s[68:69], s[0:1], 0xa0
	s_load_dwordx2 s[70:71], s[0:1], 0x48
	s_load_dwordx2 s[72:73], s[0:1], 0xd8
	s_load_dword s3, s[0:1], 0xe8
	v_readfirstlane_b32 s4, v0
	v_and_b32_e32 v7, 63, v0
	s_lshr_b32 s4, s4, 6
	v_lshrrev_b32_e32 v1, 3, v7
	v_and_b32_e32 v2, 7, v7
	s_lshl_b32 s5, s4, 14
	v_lshlrev_b32_e32 v5, 5, v2
	s_movk_i32 s14, 0x420
	v_mul_u32_u24_e32 v4, s14, v2
	v_lshlrev_b32_e32 v2, 4, v2
	s_movk_i32 s14, 0x84
	v_mad_u32_u24 v3, v1, s14, v2
	v_lshl_add_u32 v4, v1, 2, v4
	v_add_u32_e32 v3, s5, v3
	v_add_u32_e32 v4, s5, v4
	v_mov_b32_e32 v207, v3
	v_add_u32_e32 v208, 1056, v3
	v_add_u32_e32 v209, 2112, v3
	v_add_u32_e32 v210, 3168, v3
	v_add_u32_e32 v211, 4224, v3
	v_add_u32_e32 v212, 5280, v3
	v_add_u32_e32 v213, 6336, v3
	v_add_u32_e32 v214, 7392, v3
	s_waitcnt lgkmcnt(0)
	s_sub_u32 s5, s2, 8
	s_lshl_b32 s5, s5, 3
	s_add_u32 s20, s5, s4
	s_sub_u32 s21, s3, 8
	s_lshl_b32 s21, s21, 3
	s_add_u32 s20, s20, 0x10b8
	s_cmp_ge_u32 s20, 0x5600
	s_cbranch_scc1 .Lrc_p3call
	s_mov_b32 s42, 0
	s_mov_b32 s43, 0
	s_mov_b32 s26, s20
	s_cmp_lt_u32 s26, 0x2c00
	s_cbranch_scc1 .Ltrp3_i1_s0
	s_sub_u32 s26, s26, 0x2c00
	s_cmp_lt_u32 s26, 0x1600
	s_cbranch_scc1 .Ltrp3_i1_s1
	s_sub_u32 s26, s26, 0x1600
	s_cmp_lt_u32 s26, 0x800
	s_cbranch_scc1 .Ltrp3_i1_s2
	s_sub_u32 s26, s26, 0x800
	s_cmp_lt_u32 s26, 0x400
	s_cbranch_scc1 .Ltrp3_i1_s3
	s_sub_u32 s26, s26, 0x400
	s_cmp_lt_u32 s26, 0x400
	s_cbranch_scc1 .Ltrp3_i1_s4
	s_sub_u32 s26, s26, 0x400
	s_cmp_lt_u32 s26, 0x200
	s_cbranch_scc1 .Ltrp3_i1_s5
	s_sub_u32 s26, s26, 0x200
	s_branch .Ltrp3_i1_s6
